# SwiGLU epilogue: same per-element operations issued four elements abreast (no dependent trans->VALU pairs, no s_nop); hot loops at unchanged code alignment
# speedup vs baseline: 1.0129x; 1.0105x over previous
; __device__ __forceinline__ unsigned pk2(float lo, float hi) { unsigned r; asm("v_cvt_pk_bf16_f32 %0, %1, %2" : "=v"(r) : "v"(lo), "v"(hi)); return r; }
; __device__ __forceinline__ float siluf(float v) { return v * __builtin_amdgcn_rcpf(1.f + __expf(-v)); }
;     __device__ __forceinline__ void operator()(const f32x4 (&acc)[2][2][4][2], const Unit& u, int wr, int wc, int fr, int fq) const {
; #pragma unroll
;         for (int ai = 0; ai < 2; ++ai)
; #pragma unroll
;             for (int m = 0; m < 4; ++m) {
;                 const int row = u.pm * 256 + ai * 128 + wr * 64 + m * 16 + fr;
;                 const f32x4 g0 = acc[ai][0][m][0], u0 = acc[ai][0][m][1], g1 = acc[ai][1][m][0], u1 = acc[ai][1][m][1];
;                 u32x4 w;
;                 w.x = pk2(siluf(g0[0]) * u0[0], siluf(g0[1]) * u0[1]); w.y = pk2(siluf(g0[2]) * u0[2], siluf(g0[3]) * u0[3]);
;                 w.z = pk2(siluf(g1[0]) * u1[0], siluf(g1[1]) * u1[1]); w.w = pk2(siluf(g1[2]) * u1[2], siluf(g1[3]) * u1[3]);
;                 *(u32x4*)(act + (size_t)row * DFF + u.pn * 128 + wc * 32 + 8 * fq) = w;
;             }
;     }
.Lkuq_epi_full:
	v_mul_f32_e32 v202, 0xbfb8aa3b, v126
	v_mul_f32_e32 v203, 0xbfb8aa3b, v127
	v_mul_f32_e32 v204, 0xbfb8aa3b, v128
	v_mul_f32_e32 v205, 0xbfb8aa3b, v129
	v_exp_f32_e32 v202, v202
	v_exp_f32_e32 v203, v203
	v_exp_f32_e32 v204, v204
	v_exp_f32_e32 v205, v205
	v_add_f32_e32 v202, 1.0, v202
	v_add_f32_e32 v203, 1.0, v203
	v_add_f32_e32 v204, 1.0, v204
	v_add_f32_e32 v205, 1.0, v205
	v_rcp_f32_e32 v202, v202
	v_rcp_f32_e32 v203, v203
	v_rcp_f32_e32 v204, v204
	v_rcp_f32_e32 v205, v205
	v_mul_f32_e32 v202, v126, v202
	v_mul_f32_e32 v203, v127, v203
	v_mul_f32_e32 v204, v128, v204
	v_mul_f32_e32 v205, v129, v205
	v_mul_f32_e32 v202, v122, v202
	v_mul_f32_e32 v203, v123, v203
	v_mul_f32_e32 v204, v124, v204
	v_mul_f32_e32 v205, v125, v205
	v_mul_f32_e32 v210, 0xbfb8aa3b, v118
	v_mul_f32_e32 v211, 0xbfb8aa3b, v119
	v_mul_f32_e32 v212, 0xbfb8aa3b, v120
	v_mul_f32_e32 v213, 0xbfb8aa3b, v121
	v_exp_f32_e32 v210, v210
	v_exp_f32_e32 v211, v211
	v_exp_f32_e32 v212, v212
	v_exp_f32_e32 v213, v213
	v_add_f32_e32 v210, 1.0, v210
	v_add_f32_e32 v211, 1.0, v211
	v_add_f32_e32 v212, 1.0, v212
	v_add_f32_e32 v213, 1.0, v213
	v_rcp_f32_e32 v210, v210
	v_rcp_f32_e32 v211, v211
	v_rcp_f32_e32 v212, v212
	v_rcp_f32_e32 v213, v213
	v_mul_f32_e32 v210, v118, v210
	v_mul_f32_e32 v211, v119, v211
	v_mul_f32_e32 v212, v120, v212
	v_mul_f32_e32 v213, v121, v213
	v_mul_f32_e32 v210, v114, v210
	v_mul_f32_e32 v211, v115, v211
	v_mul_f32_e32 v212, v116, v212
	v_mul_f32_e32 v213, v117, v213
	v_cvt_pk_bf16_f32 v122, v202, v203
	v_cvt_pk_bf16_f32 v123, v204, v205
	v_cvt_pk_bf16_f32 v124, v210, v211
	v_cvt_pk_bf16_f32 v125, v212, v213
	s_lshl_b32 s19, s28, 8
	s_lshl_b32 s26, s26, 7
	v_add_u32_e32 v155, s19, v143
	s_movk_i32 s21, 0x1600
	s_ashr_i32 s27, s26, 31
	s_lshl_b64 s[26:27], s[26:27], 1
	s_andn2_b64 vcc, exec, s[6:7]
	v_mov_b64_e32 v[114:115], s[14:15]
	v_mad_i64_i32 v[116:117], s[30:31], v155, s21, v[114:115]
	v_lshl_add_u64 v[116:117], v[116:117], 0, s[26:27]
	v_lshl_add_u64 v[116:117], v[116:117], 0, s[64:65]
	v_lshl_add_u64 v[116:117], v[116:117], 0, v[0:1]
	global_store_dwordx4 v[116:117], v[122:125], off
	v_mul_f32_e32 v202, 0xbfb8aa3b, v110
	v_mul_f32_e32 v203, 0xbfb8aa3b, v111
	v_mul_f32_e32 v204, 0xbfb8aa3b, v112
	v_mul_f32_e32 v205, 0xbfb8aa3b, v113
	v_exp_f32_e32 v202, v202
	v_exp_f32_e32 v203, v203
	v_exp_f32_e32 v204, v204
	v_exp_f32_e32 v205, v205
	v_add_f32_e32 v202, 1.0, v202
	v_add_f32_e32 v203, 1.0, v203
	v_add_f32_e32 v204, 1.0, v204
	v_add_f32_e32 v205, 1.0, v205
	v_rcp_f32_e32 v202, v202
	v_rcp_f32_e32 v203, v203
	v_rcp_f32_e32 v204, v204
	v_rcp_f32_e32 v205, v205
	v_mul_f32_e32 v202, v110, v202
	v_mul_f32_e32 v203, v111, v203
	v_mul_f32_e32 v204, v112, v204
	v_mul_f32_e32 v205, v113, v205
	v_mul_f32_e32 v202, v106, v202
	v_mul_f32_e32 v203, v107, v203
	v_mul_f32_e32 v204, v108, v204
	v_mul_f32_e32 v205, v109, v205
	v_mul_f32_e32 v210, 0xbfb8aa3b, v102
	v_mul_f32_e32 v211, 0xbfb8aa3b, v103
	v_mul_f32_e32 v212, 0xbfb8aa3b, v104
	v_mul_f32_e32 v213, 0xbfb8aa3b, v105
	v_exp_f32_e32 v210, v210
	v_exp_f32_e32 v211, v211
	v_exp_f32_e32 v212, v212
	v_exp_f32_e32 v213, v213
	v_add_f32_e32 v210, 1.0, v210
	v_add_f32_e32 v211, 1.0, v211
	v_add_f32_e32 v212, 1.0, v212
	v_add_f32_e32 v213, 1.0, v213
	v_rcp_f32_e32 v210, v210
	v_rcp_f32_e32 v211, v211
	v_rcp_f32_e32 v212, v212
	v_rcp_f32_e32 v213, v213
	v_mul_f32_e32 v210, v102, v210
	v_mul_f32_e32 v211, v103, v211
	v_mul_f32_e32 v212, v104, v212
	v_mul_f32_e32 v213, v105, v213
	v_mul_f32_e32 v210, v98, v210
	v_mul_f32_e32 v211, v99, v211
	v_mul_f32_e32 v212, v100, v212
	v_mul_f32_e32 v213, v101, v213
	v_cvt_pk_bf16_f32 v106, v202, v203
	v_cvt_pk_bf16_f32 v107, v204, v205
	v_cvt_pk_bf16_f32 v108, v210, v211
	v_cvt_pk_bf16_f32 v109, v212, v213
	v_add_u32_e32 v116, s19, v147
	v_mad_i64_i32 v[98:99], s[30:31], v116, s21, v[114:115]
	v_lshl_add_u64 v[98:99], v[98:99], 0, s[26:27]
	v_lshl_add_u64 v[98:99], v[98:99], 0, s[64:65]
; __device__ __forceinline__ unsigned pk2(float lo, float hi) { unsigned r; asm("v_cvt_pk_bf16_f32 %0, %1, %2" : "=v"(r) : "v"(lo), "v"(hi)); return r; }
; __device__ __forceinline__ float siluf(float v) { return v * __builtin_amdgcn_rcpf(1.f + __expf(-v)); }
;     __device__ __forceinline__ void operator()(const f32x4 (&acc)[2][2][4][2], const Unit& u, int wr, int wc, int fr, int fq) const {
; #pragma unroll
;         for (int ai = 0; ai < 2; ++ai)
; #pragma unroll
;             for (int m = 0; m < 4; ++m) {
;                 const int row = u.pm * 256 + ai * 128 + wr * 64 + m * 16 + fr;
;                 const f32x4 g0 = acc[ai][0][m][0], u0 = acc[ai][0][m][1], g1 = acc[ai][1][m][0], u1 = acc[ai][1][m][1];
;                 u32x4 w;
;                 w.x = pk2(siluf(g0[0]) * u0[0], siluf(g0[1]) * u0[1]); w.y = pk2(siluf(g0[2]) * u0[2], siluf(g0[3]) * u0[3]);
;                 w.z = pk2(siluf(g1[0]) * u1[0], siluf(g1[1]) * u1[1]); w.w = pk2(siluf(g1[2]) * u1[2], siluf(g1[3]) * u1[3]);
;                 *(u32x4*)(act + (size_t)row * DFF + u.pn * 128 + wc * 32 + 8 * fq) = w;
;             }
;     }
	v_lshl_add_u64 v[98:99], v[98:99], 0, v[0:1]
	global_store_dwordx4 v[98:99], v[106:109], off
	v_mul_f32_e32 v202, 0xbfb8aa3b, v94
	v_mul_f32_e32 v203, 0xbfb8aa3b, v95
	v_mul_f32_e32 v204, 0xbfb8aa3b, v96
	v_mul_f32_e32 v205, 0xbfb8aa3b, v97
	v_exp_f32_e32 v202, v202
	v_exp_f32_e32 v203, v203
	v_exp_f32_e32 v204, v204
	v_exp_f32_e32 v205, v205
	v_add_f32_e32 v202, 1.0, v202
	v_add_f32_e32 v203, 1.0, v203
	v_add_f32_e32 v204, 1.0, v204
	v_add_f32_e32 v205, 1.0, v205
	v_rcp_f32_e32 v202, v202
	v_rcp_f32_e32 v203, v203
	v_rcp_f32_e32 v204, v204
	v_rcp_f32_e32 v205, v205
	v_mul_f32_e32 v202, v94, v202
	v_mul_f32_e32 v203, v95, v203
	v_mul_f32_e32 v204, v96, v204
	v_mul_f32_e32 v205, v97, v205
	v_mul_f32_e32 v202, v90, v202
	v_mul_f32_e32 v203, v91, v203
	v_mul_f32_e32 v204, v92, v204
	v_mul_f32_e32 v205, v93, v205
	v_mul_f32_e32 v210, 0xbfb8aa3b, v86
	v_mul_f32_e32 v211, 0xbfb8aa3b, v87
	v_mul_f32_e32 v212, 0xbfb8aa3b, v88
	v_mul_f32_e32 v213, 0xbfb8aa3b, v89
	v_exp_f32_e32 v210, v210
	v_exp_f32_e32 v211, v211
	v_exp_f32_e32 v212, v212
	v_exp_f32_e32 v213, v213
	v_add_f32_e32 v210, 1.0, v210
	v_add_f32_e32 v211, 1.0, v211
	v_add_f32_e32 v212, 1.0, v212
	v_add_f32_e32 v213, 1.0, v213
	v_rcp_f32_e32 v210, v210
	v_rcp_f32_e32 v211, v211
	v_rcp_f32_e32 v212, v212
	v_rcp_f32_e32 v213, v213
	v_mul_f32_e32 v210, v86, v210
	v_mul_f32_e32 v211, v87, v211
	v_mul_f32_e32 v212, v88, v212
	v_mul_f32_e32 v213, v89, v213
	v_mul_f32_e32 v210, v82, v210
	v_mul_f32_e32 v211, v83, v211
	v_mul_f32_e32 v212, v84, v212
	v_mul_f32_e32 v213, v85, v213
	v_cvt_pk_bf16_f32 v90, v202, v203
	v_cvt_pk_bf16_f32 v91, v204, v205
	v_cvt_pk_bf16_f32 v92, v210, v211
	v_cvt_pk_bf16_f32 v93, v212, v213
	v_add_u32_e32 v98, s19, v148
	v_mad_i64_i32 v[82:83], s[30:31], v98, s21, v[114:115]
	v_lshl_add_u64 v[82:83], v[82:83], 0, s[26:27]
	v_lshl_add_u64 v[82:83], v[82:83], 0, s[64:65]
	v_lshl_add_u64 v[82:83], v[82:83], 0, v[0:1]
	global_store_dwordx4 v[82:83], v[90:93], off
	v_mul_f32_e32 v202, 0xbfb8aa3b, v78
	v_mul_f32_e32 v203, 0xbfb8aa3b, v79
	v_mul_f32_e32 v204, 0xbfb8aa3b, v80
	v_mul_f32_e32 v205, 0xbfb8aa3b, v81
	v_exp_f32_e32 v202, v202
	v_exp_f32_e32 v203, v203
	v_exp_f32_e32 v204, v204
	v_exp_f32_e32 v205, v205
	v_add_f32_e32 v202, 1.0, v202
	v_add_f32_e32 v203, 1.0, v203
	v_add_f32_e32 v204, 1.0, v204
	v_add_f32_e32 v205, 1.0, v205
	v_rcp_f32_e32 v202, v202
	v_rcp_f32_e32 v203, v203
	v_rcp_f32_e32 v204, v204
	v_rcp_f32_e32 v205, v205
	v_mul_f32_e32 v202, v78, v202
	v_mul_f32_e32 v203, v79, v203
	v_mul_f32_e32 v204, v80, v204
	v_mul_f32_e32 v205, v81, v205
	v_mul_f32_e32 v202, v74, v202
	v_mul_f32_e32 v203, v75, v203
	v_mul_f32_e32 v204, v76, v204
	v_mul_f32_e32 v205, v77, v205
	v_mul_f32_e32 v210, 0xbfb8aa3b, v70
	v_mul_f32_e32 v211, 0xbfb8aa3b, v71
	v_mul_f32_e32 v212, 0xbfb8aa3b, v72
	v_mul_f32_e32 v213, 0xbfb8aa3b, v73
	v_exp_f32_e32 v210, v210
	v_exp_f32_e32 v211, v211
	v_exp_f32_e32 v212, v212
	v_exp_f32_e32 v213, v213
	v_add_f32_e32 v210, 1.0, v210
	v_add_f32_e32 v211, 1.0, v211
	v_add_f32_e32 v212, 1.0, v212
	v_add_f32_e32 v213, 1.0, v213
	v_rcp_f32_e32 v210, v210
	v_rcp_f32_e32 v211, v211
	v_rcp_f32_e32 v212, v212
	v_rcp_f32_e32 v213, v213
	v_mul_f32_e32 v210, v70, v210
	v_mul_f32_e32 v211, v71, v211
	v_mul_f32_e32 v212, v72, v212
	v_mul_f32_e32 v213, v73, v213
	v_mul_f32_e32 v210, v66, v210
	v_mul_f32_e32 v211, v67, v211
	v_mul_f32_e32 v212, v68, v212
	v_mul_f32_e32 v213, v69, v213
	v_cvt_pk_bf16_f32 v74, v202, v203
	v_cvt_pk_bf16_f32 v75, v204, v205
	v_cvt_pk_bf16_f32 v76, v210, v211
	v_cvt_pk_bf16_f32 v77, v212, v213
	v_add_u32_e32 v82, s19, v149
	v_mad_i64_i32 v[66:67], s[30:31], v82, s21, v[114:115]
	v_lshl_add_u64 v[66:67], v[66:67], 0, s[26:27]
	v_lshl_add_u64 v[66:67], v[66:67], 0, s[64:65]
	v_lshl_add_u64 v[66:67], v[66:67], 0, v[0:1]
	global_store_dwordx4 v[66:67], v[74:77], off
	s_and_b32 s98, s101, 7
	s_cmp_eq_u32 s98, 5
	s_cbranch_scc1 .Lku_epi_skip1
	s_branch .Lku_epi_g4

; __device__ __forceinline__ unsigned pk2(float lo, float hi) { unsigned r; asm("v_cvt_pk_bf16_f32 %0, %1, %2" : "=v"(r) : "v"(lo), "v"(hi)); return r; }
; __device__ __forceinline__ float siluf(float v) { return v * __builtin_amdgcn_rcpf(1.f + __expf(-v)); }
;     __device__ __forceinline__ void operator()(const f32x4 (&acc)[2][2][4][2], const Unit& u, int wr, int wc, int fr, int fq) const {
; #pragma unroll
;         for (int ai = 0; ai < 2; ++ai)
; #pragma unroll
;             for (int m = 0; m < 4; ++m) {
;                 const int row = u.pm * 256 + ai * 128 + wr * 64 + m * 16 + fr;
;                 const f32x4 g0 = acc[ai][0][m][0], u0 = acc[ai][0][m][1], g1 = acc[ai][1][m][0], u1 = acc[ai][1][m][1];
;                 u32x4 w;
;                 w.x = pk2(siluf(g0[0]) * u0[0], siluf(g0[1]) * u0[1]); w.y = pk2(siluf(g0[2]) * u0[2], siluf(g0[3]) * u0[3]);
;                 w.z = pk2(siluf(g1[0]) * u1[0], siluf(g1[1]) * u1[1]); w.w = pk2(siluf(g1[2]) * u1[2], siluf(g1[3]) * u1[3]);
;                 *(u32x4*)(act + (size_t)row * DFF + u.pn * 128 + wc * 32 + 8 * fq) = w;
;             }
;     }
.Lku_epi_g4:
	v_mul_f32_e32 v202, 0xbfb8aa3b, v62
	v_mul_f32_e32 v203, 0xbfb8aa3b, v63
	v_mul_f32_e32 v204, 0xbfb8aa3b, v64
	v_mul_f32_e32 v205, 0xbfb8aa3b, v65
	v_exp_f32_e32 v202, v202
	v_exp_f32_e32 v203, v203
	v_exp_f32_e32 v204, v204
	v_exp_f32_e32 v205, v205
	v_add_f32_e32 v202, 1.0, v202
	v_add_f32_e32 v203, 1.0, v203
	v_add_f32_e32 v204, 1.0, v204
	v_add_f32_e32 v205, 1.0, v205
	v_rcp_f32_e32 v202, v202
	v_rcp_f32_e32 v203, v203
	v_rcp_f32_e32 v204, v204
	v_rcp_f32_e32 v205, v205
	v_mul_f32_e32 v202, v62, v202
	v_mul_f32_e32 v203, v63, v203
	v_mul_f32_e32 v204, v64, v204
	v_mul_f32_e32 v205, v65, v205
	v_mul_f32_e32 v202, v58, v202
	v_mul_f32_e32 v203, v59, v203
	v_mul_f32_e32 v204, v60, v204
	v_mul_f32_e32 v205, v61, v205
	v_mul_f32_e32 v210, 0xbfb8aa3b, v54
	v_mul_f32_e32 v211, 0xbfb8aa3b, v55
	v_mul_f32_e32 v212, 0xbfb8aa3b, v56
	v_mul_f32_e32 v213, 0xbfb8aa3b, v57
	v_exp_f32_e32 v210, v210
	v_exp_f32_e32 v211, v211
	v_exp_f32_e32 v212, v212
	v_exp_f32_e32 v213, v213
	v_add_f32_e32 v210, 1.0, v210
	v_add_f32_e32 v211, 1.0, v211
	v_add_f32_e32 v212, 1.0, v212
	v_add_f32_e32 v213, 1.0, v213
	v_rcp_f32_e32 v210, v210
	v_rcp_f32_e32 v211, v211
	v_rcp_f32_e32 v212, v212
	v_rcp_f32_e32 v213, v213
	v_mul_f32_e32 v210, v54, v210
	v_mul_f32_e32 v211, v55, v211
	v_mul_f32_e32 v212, v56, v212
	v_mul_f32_e32 v213, v57, v213
	v_mul_f32_e32 v210, v50, v210
	v_mul_f32_e32 v211, v51, v211
	v_mul_f32_e32 v212, v52, v212
	v_mul_f32_e32 v213, v53, v213
	v_cvt_pk_bf16_f32 v58, v202, v203
	v_cvt_pk_bf16_f32 v59, v204, v205
	v_cvt_pk_bf16_f32 v60, v210, v211
	v_cvt_pk_bf16_f32 v61, v212, v213
	v_add_u32_e32 v66, s19, v150
	v_mad_i64_i32 v[50:51], s[30:31], v66, s21, v[114:115]
	v_lshl_add_u64 v[50:51], v[50:51], 0, s[26:27]
	v_lshl_add_u64 v[50:51], v[50:51], 0, s[64:65]
	v_lshl_add_u64 v[50:51], v[50:51], 0, v[0:1]
	global_store_dwordx4 v[50:51], v[58:61], off
	v_mul_f32_e32 v202, 0xbfb8aa3b, v46
	v_mul_f32_e32 v203, 0xbfb8aa3b, v47
	v_mul_f32_e32 v204, 0xbfb8aa3b, v48
	v_mul_f32_e32 v205, 0xbfb8aa3b, v49
	v_exp_f32_e32 v202, v202
	v_exp_f32_e32 v203, v203
	v_exp_f32_e32 v204, v204
	v_exp_f32_e32 v205, v205
	v_add_f32_e32 v202, 1.0, v202
	v_add_f32_e32 v203, 1.0, v203
	v_add_f32_e32 v204, 1.0, v204
	v_add_f32_e32 v205, 1.0, v205
	v_rcp_f32_e32 v202, v202
	v_rcp_f32_e32 v203, v203
	v_rcp_f32_e32 v204, v204
	v_rcp_f32_e32 v205, v205
	v_mul_f32_e32 v202, v46, v202
	v_mul_f32_e32 v203, v47, v203
	v_mul_f32_e32 v204, v48, v204
	v_mul_f32_e32 v205, v49, v205
	v_mul_f32_e32 v202, v42, v202
	v_mul_f32_e32 v203, v43, v203
	v_mul_f32_e32 v204, v44, v204
	v_mul_f32_e32 v205, v45, v205
	v_mul_f32_e32 v210, 0xbfb8aa3b, v38
	v_mul_f32_e32 v211, 0xbfb8aa3b, v39
	v_mul_f32_e32 v212, 0xbfb8aa3b, v40
	v_mul_f32_e32 v213, 0xbfb8aa3b, v41
	v_exp_f32_e32 v210, v210
	v_exp_f32_e32 v211, v211
	v_exp_f32_e32 v212, v212
	v_exp_f32_e32 v213, v213
	v_add_f32_e32 v210, 1.0, v210
	v_add_f32_e32 v211, 1.0, v211
	v_add_f32_e32 v212, 1.0, v212
	v_add_f32_e32 v213, 1.0, v213
	v_rcp_f32_e32 v210, v210
	v_rcp_f32_e32 v211, v211
	v_rcp_f32_e32 v212, v212
	v_rcp_f32_e32 v213, v213
	v_mul_f32_e32 v210, v38, v210
	v_mul_f32_e32 v211, v39, v211
	v_mul_f32_e32 v212, v40, v212
	v_mul_f32_e32 v213, v41, v213
	v_mul_f32_e32 v210, v34, v210
	v_mul_f32_e32 v211, v35, v211
	v_mul_f32_e32 v212, v36, v212
	v_mul_f32_e32 v213, v37, v213
	v_cvt_pk_bf16_f32 v42, v202, v203
	v_cvt_pk_bf16_f32 v43, v204, v205
	v_cvt_pk_bf16_f32 v44, v210, v211
	v_cvt_pk_bf16_f32 v45, v212, v213
	v_add_u32_e32 v50, s19, v151
	v_mad_i64_i32 v[34:35], s[30:31], v50, s21, v[114:115]
	v_lshl_add_u64 v[34:35], v[34:35], 0, s[26:27]
	v_lshl_add_u64 v[34:35], v[34:35], 0, s[64:65]
	v_lshl_add_u64 v[34:35], v[34:35], 0, v[0:1]
	global_store_dwordx4 v[34:35], v[42:45], off
; __device__ __forceinline__ unsigned pk2(float lo, float hi) { unsigned r; asm("v_cvt_pk_bf16_f32 %0, %1, %2" : "=v"(r) : "v"(lo), "v"(hi)); return r; }
; __device__ __forceinline__ float siluf(float v) { return v * __builtin_amdgcn_rcpf(1.f + __expf(-v)); }
;     __device__ __forceinline__ void operator()(const f32x4 (&acc)[2][2][4][2], const Unit& u, int wr, int wc, int fr, int fq) const {
; #pragma unroll
;         for (int ai = 0; ai < 2; ++ai)
; #pragma unroll
;             for (int m = 0; m < 4; ++m) {
;                 const int row = u.pm * 256 + ai * 128 + wr * 64 + m * 16 + fr;
;                 const f32x4 g0 = acc[ai][0][m][0], u0 = acc[ai][0][m][1], g1 = acc[ai][1][m][0], u1 = acc[ai][1][m][1];
;                 u32x4 w;
;                 w.x = pk2(siluf(g0[0]) * u0[0], siluf(g0[1]) * u0[1]); w.y = pk2(siluf(g0[2]) * u0[2], siluf(g0[3]) * u0[3]);
;                 w.z = pk2(siluf(g1[0]) * u1[0], siluf(g1[1]) * u1[1]); w.w = pk2(siluf(g1[2]) * u1[2], siluf(g1[3]) * u1[3]);
;                 *(u32x4*)(act + (size_t)row * DFF + u.pn * 128 + wc * 32 + 8 * fq) = w;
;             }
;     }
	v_mul_f32_e32 v202, 0xbfb8aa3b, v30
	v_mul_f32_e32 v203, 0xbfb8aa3b, v31
	v_mul_f32_e32 v204, 0xbfb8aa3b, v32
	v_mul_f32_e32 v205, 0xbfb8aa3b, v33
	v_exp_f32_e32 v202, v202
	v_exp_f32_e32 v203, v203
	v_exp_f32_e32 v204, v204
	v_exp_f32_e32 v205, v205
	v_add_f32_e32 v202, 1.0, v202
	v_add_f32_e32 v203, 1.0, v203
	v_add_f32_e32 v204, 1.0, v204
	v_add_f32_e32 v205, 1.0, v205
	v_rcp_f32_e32 v202, v202
	v_rcp_f32_e32 v203, v203
	v_rcp_f32_e32 v204, v204
	v_rcp_f32_e32 v205, v205
	v_mul_f32_e32 v202, v30, v202
	v_mul_f32_e32 v203, v31, v203
	v_mul_f32_e32 v204, v32, v204
	v_mul_f32_e32 v205, v33, v205
	v_mul_f32_e32 v202, v26, v202
	v_mul_f32_e32 v203, v27, v203
	v_mul_f32_e32 v204, v28, v204
	v_mul_f32_e32 v205, v29, v205
	v_mul_f32_e32 v210, 0xbfb8aa3b, v22
	v_mul_f32_e32 v211, 0xbfb8aa3b, v23
	v_mul_f32_e32 v212, 0xbfb8aa3b, v24
	v_mul_f32_e32 v213, 0xbfb8aa3b, v25
	v_exp_f32_e32 v210, v210
	v_exp_f32_e32 v211, v211
	v_exp_f32_e32 v212, v212
	v_exp_f32_e32 v213, v213
	v_add_f32_e32 v210, 1.0, v210
	v_add_f32_e32 v211, 1.0, v211
	v_add_f32_e32 v212, 1.0, v212
	v_add_f32_e32 v213, 1.0, v213
	v_rcp_f32_e32 v210, v210
	v_rcp_f32_e32 v211, v211
	v_rcp_f32_e32 v212, v212
	v_rcp_f32_e32 v213, v213
	v_mul_f32_e32 v210, v22, v210
	v_mul_f32_e32 v211, v23, v211
	v_mul_f32_e32 v212, v24, v212
	v_mul_f32_e32 v213, v25, v213
	v_mul_f32_e32 v210, v18, v210
	v_mul_f32_e32 v211, v19, v211
	v_mul_f32_e32 v212, v20, v212
	v_mul_f32_e32 v213, v21, v213
	v_cvt_pk_bf16_f32 v26, v202, v203
	v_cvt_pk_bf16_f32 v27, v204, v205
	v_cvt_pk_bf16_f32 v28, v210, v211
	v_cvt_pk_bf16_f32 v29, v212, v213
	v_add_u32_e32 v34, s19, v152
	v_mad_i64_i32 v[18:19], s[30:31], v34, s21, v[114:115]
	v_lshl_add_u64 v[18:19], v[18:19], 0, s[26:27]
	v_lshl_add_u64 v[18:19], v[18:19], 0, s[64:65]
	v_lshl_add_u64 v[18:19], v[18:19], 0, v[0:1]
	global_store_dwordx4 v[18:19], v[26:29], off
	v_mul_f32_e32 v202, 0xbfb8aa3b, v14
	v_mul_f32_e32 v203, 0xbfb8aa3b, v15
	v_mul_f32_e32 v204, 0xbfb8aa3b, v16
	v_mul_f32_e32 v205, 0xbfb8aa3b, v17
	v_exp_f32_e32 v202, v202
	v_exp_f32_e32 v203, v203
	v_exp_f32_e32 v204, v204
	v_exp_f32_e32 v205, v205
	v_add_f32_e32 v202, 1.0, v202
	v_add_f32_e32 v203, 1.0, v203
	v_add_f32_e32 v204, 1.0, v204
	v_add_f32_e32 v205, 1.0, v205
	v_rcp_f32_e32 v202, v202
	v_rcp_f32_e32 v203, v203
	v_rcp_f32_e32 v204, v204
	v_rcp_f32_e32 v205, v205
	v_mul_f32_e32 v202, v14, v202
	v_mul_f32_e32 v203, v15, v203
	v_mul_f32_e32 v204, v16, v204
	v_mul_f32_e32 v205, v17, v205
	v_mul_f32_e32 v202, v10, v202
	v_mul_f32_e32 v203, v11, v203
	v_mul_f32_e32 v204, v12, v204
	v_mul_f32_e32 v205, v13, v205
	v_mul_f32_e32 v210, 0xbfb8aa3b, v6
	v_mul_f32_e32 v211, 0xbfb8aa3b, v7
	v_mul_f32_e32 v212, 0xbfb8aa3b, v8
	v_mul_f32_e32 v213, 0xbfb8aa3b, v9
	v_exp_f32_e32 v210, v210
	v_exp_f32_e32 v211, v211
	v_exp_f32_e32 v212, v212
	v_exp_f32_e32 v213, v213
	v_add_f32_e32 v210, 1.0, v210
	v_add_f32_e32 v211, 1.0, v211
	v_add_f32_e32 v212, 1.0, v212
	v_add_f32_e32 v213, 1.0, v213
	v_rcp_f32_e32 v210, v210
	v_rcp_f32_e32 v211, v211
	v_rcp_f32_e32 v212, v212
	v_rcp_f32_e32 v213, v213
	v_mul_f32_e32 v210, v6, v210
	v_mul_f32_e32 v211, v7, v211
	v_mul_f32_e32 v212, v8, v212
	v_mul_f32_e32 v213, v9, v213
	v_mul_f32_e32 v210, v2, v210
	v_mul_f32_e32 v211, v3, v211
	v_mul_f32_e32 v212, v4, v212
	v_mul_f32_e32 v213, v5, v213
	v_cvt_pk_bf16_f32 v10, v202, v203
	v_cvt_pk_bf16_f32 v11, v204, v205
	v_cvt_pk_bf16_f32 v12, v210, v211
	v_cvt_pk_bf16_f32 v13, v212, v213
	v_add_u32_e32 v18, s19, v153
	v_mad_i64_i32 v[2:3], s[30:31], v18, s21, v[114:115]
	v_lshl_add_u64 v[2:3], v[2:3], 0, s[26:27]
	v_lshl_add_u64 v[2:3], v[2:3], 0, s[64:65]
	v_lshl_add_u64 v[2:3], v[2:3], 0, v[0:1]
	s_mov_b64 s[26:27], -1
	global_store_dwordx4 v[2:3], v[10:13], off
	s_branch .Lku_epi_end

; #define PG8_STAGE(bufoff, gbase, voff) do { _Pragma("unroll") for (int _i = 0; _i < 2; ++_i) \
;         __builtin_amdgcn_global_load_lds((const unsigned*)((const char*)(gbase) + (voff)[_i]), (PG8_LAS unsigned*)(lds + (bufoff) + ldsw + _i * 8192), 16, 0, 0); } while (0)
; #define PG8_BAR __builtin_amdgcn_s_barrier()
; template <class Epi, class Sched, bool ALIGN_EPI = false, bool SP2 = false>
; __device__ __forceinline__ void gemm_phase(PG8_LAS unsigned char* lds, const Gemm g, const Sched& S, const Epi& E) {
;     ...
;         PG8_STAGE(PG8_SB(1, 0), cB + kstep, voffB); PG8_STAGE(PG8_SA(1, 0), cA + kstep, voffA); PG8_STAGE(PG8_SB(1, 1), cB + hstep + kstep, voffB);
;         PG8_WAIT_V(6); PG8_BAR;
;     } else {
;         PG8_STAGE(PG8_SB(0, 0), cB, voffB); PG8_STAGE(PG8_SA(0, 0), cA, voffA); PG8_STAGE(PG8_SB(0, 1), cB + hstep, voffB); PG8_STAGE(PG8_SA(0, 1), cA + hstep, voffA);
;         if (wr == 1) PG8_BAR;
;         PG8_WAIT_V(4); PG8_BAR;
;         PG8_STAGE(PG8_SB(1, 0), cB + kstep, voffB); PG8_STAGE(PG8_SA(1, 0), cA + kstep, voffA); PG8_STAGE(PG8_SB(1, 1), cB + hstep + kstep, voffB);
;         PG8_WAIT_V(6); PG8_BAR;
;     __device__ __forceinline__ void operator()(const f32x4 (&acc)[2][2][4][2], const Unit& u, int wr, int wc, int fr, int fq) const {
;         const int pm = u.pm + pm0, pn = u.pn + pn0;
;         const bool lat = pm < 64; const int b = lat ? (pm >> 3) : (pm - 64); const int tokb = lat ? (pm & 7) * 256 : 2048;
;         const int rl0 = wr * 64 + fr, cl0 = wc * 32 + 4 * fq;
;         if (pn < 5) {
;             bf16_t* base; int ld;
;             if (pn < 4) { base = swq + pn * 256; ld = 1024; } else { base = swk; ld = 256; }
;             base += (size_t)(pm * 256 + rl0) * ld + cl0;
;             const float rot = lat ? 1.f : 0.f;
; #pragma unroll
;             for (int ai = 0; ai < 2; ++ai)
; #pragma unroll
;                 for (int m = 0; m < 4; ++m) {
;                     const int tok = tokb + rl0 + ai * 128 + m * 16;
;                     const float pos = rot * (float)((wc & 1) ? (tok & 63) : (tok >> 6));
;                     bf16_t* rp = base + (size_t)(ai * 128 + m * 16) * ld;
;                     float cs[4], sn[4];
; #pragma unroll
;                     for (int j = 0; j < 4; ++j) { const float a = pos * __builtin_amdgcn_exp2f(-(float)(4 * fq + j) * 0.830482023721841f); cs[j] = __cosf(a); sn[j] = __sinf(a); }
.LBB0_182:
	s_add_u32 s79, s6, 0x7f00000
	s_addc_u32 s80, s7, 0
	s_add_u32 s81, s6, 0x9f00000
	s_addc_u32 s82, s7, 0
	s_add_u32 s16, s6, 0xa800000
	s_addc_u32 s17, s7, 0
	s_and_b32 s20, s11, 3
	s_add_i32 m0, s50, 0x18000
	v_lshl_add_u64 v[8:9], v[8:9], 0, s[66:67]
	s_lshl_b32 s19, s18, 13
	s_lshl_b32 s21, s20, 12
	s_waitcnt vmcnt(2)
	s_barrier
	global_load_lds_dwordx4 v[8:9], off
	v_lshl_add_u64 v[6:7], v[6:7], 0, s[66:67]
	s_add_i32 m0, s50, 0x1a000
	s_add_i32 s83, s50, 0x8000
	s_add_i32 s84, s50, 0xa000
	global_load_lds_dwordx4 v[6:7], off
	v_lshl_add_u64 v[2:3], v[2:3], 0, s[66:67]
	s_mov_b32 m0, s83
	s_add_u32 s6, s34, 0x40080
	global_load_lds_dwordx4 v[2:3], off
	v_lshl_add_u64 v[2:3], v[4:5], 0, s[66:67]
	s_mov_b32 m0, s84
	s_addc_u32 s7, s35, 0
	global_load_lds_dwordx4 v[2:3], off
	s_add_i32 m0, s50, 0x1c000
	v_lshl_add_u64 v[2:3], s[6:7], 0, v[132:133]
	global_load_lds_dwordx4 v[2:3], off
	v_lshl_add_u64 v[2:3], s[6:7], 0, v[130:131]
	s_add_i32 m0, s50, 0x1e000
	v_and_b32_e32 v137, 15, v12
	global_load_lds_dwordx4 v[2:3], off
	v_bfe_u32 v2, v12, 4, 2
	v_lshlrev_b32_e32 v3, 4, v2
	v_lshlrev_b32_e32 v4, 2, v12
	v_lshl_or_b32 v3, v137, 6, v3
	v_and_b32_e32 v4, 32, v4
	v_lshlrev_b32_e32 v2, 2, v2
	v_bitop3_b32 v5, v3, s19, v4 bitop3:0xde
	v_bitop3_b32 v143, v3, s21, v4 bitop3:0xde
	v_cvt_f32_ubyte0_e32 v3, v2
	v_mul_f32_e32 v3, 0xbf549a78, v3
	v_exp_f32_e32 v145, v3
	v_or_b32_e32 v3, 1, v2
	v_cvt_f32_ubyte0_e32 v3, v3
	v_mul_f32_e32 v3, 0xbf549a78, v3
	v_lshl_or_b32 v136, s20, 5, v2
	v_exp_f32_e32 v147, v3
	v_or_b32_e32 v3, 2, v2
	v_or_b32_e32 v2, 3, v2
	v_cvt_f32_ubyte0_e32 v2, v2
	v_mul_f32_e32 v2, 0xbf549a78, v2
	v_cvt_f32_ubyte0_e32 v3, v3
	v_exp_f32_e32 v208, v2
	v_lshlrev_b32_e32 v2, 14, v13
	v_mul_f32_e32 v3, 0xbf549a78, v3
	v_and_b32_e32 v2, 0xffff8000, v2
	v_exp_f32_e32 v207, v3
	v_lshl_add_u32 v2, v14, 11, v2
	v_and_b32_e32 v3, 1, v13
	v_lshl_or_b32 v2, v3, 6, v2
	v_lshl_add_u32 v148, v15, 1, v2
	v_lshlrev_b32_e32 v2, 14, v0
	v_and_b32_e32 v2, 0xffff8000, v2
	s_waitcnt vmcnt(6)
	s_cmpk_lt_u32 s9, 0x100
	v_lshl_add_u32 v2, v10, 11, v2
	v_and_b32_e32 v0, 1, v0
	v_lshl_or_b32 v134, s18, 6, v137
	s_cselect_b64 s[18:19], -1, 0
	s_bitcmp0_b32 s9, 6
	v_lshl_or_b32 v0, v0, 6, v2
	s_sext_i32_i16 s29, s8
	s_mov_b32 s11, s65
	v_ashrrev_i32_e32 v135, 31, v134
	s_mov_b32 s52, 0
	s_cselect_b64 s[6:7], -1, 0
	v_or_b32_e32 v209, 16, v137
	v_or_b32_e32 v210, 32, v137
	v_or_b32_e32 v211, 48, v137
	v_mov_b32_e32 v149, v1
	v_lshl_add_u32 v150, v11, 1, v0
	v_mov_b32_e32 v151, v1
	v_add_u32_e32 v212, 0, v5
	s_barrier
	s_branch .LBB0_185
	s_nop 0
.LBB0_183:
	s_mov_b64 s[8:9], 0
